# speedup vs baseline: 1.0157x; 1.0046x over previous
; __device__ __forceinline__ unsigned cvt_pk_bf16(float lo, float hi) { unsigned r; asm volatile("v_cvt_pk_bf16_f32 %0, %1, %2" : "=v"(r) : "v"(lo), "v"(hi)); return r; }
;     __device__ __forceinline__ void operator()(const f32x4 (&acc)[2][2][4][2], const Unit& u, int wr, int wc, int fr, int fq) const {
;     ...
;             for (int m = 0; m < 4; ++m) { bf16_t* rowp = T + (size_t)(row0 + ai * HALF + m * 16) * ldc + col0; float t[8];
; #pragma unroll
;                 for (int n = 0; n < 2; ++n) { const f32x4 a = acc[ai][0][m][n], b = acc[ai][1][m][n];
; #pragma unroll
;                     for (int e = 0; e < 4; ++e) t[4 * n + e] = a[e] * __builtin_amdgcn_rcpf(1.0f + __expf(-a[e])) * b[e]; }
;                 u32x4 w; w.x = cvt_pk_bf16(t[0], t[1]); w.y = cvt_pk_bf16(t[2], t[3]); w.z = cvt_pk_bf16(t[4], t[5]); w.w = cvt_pk_bf16(t[6], t[7]);
;                 *(u32x4*)rowp = w; }
.LBB0_340:
	v_mov_b32_e32 v164, 0xbfb8aa3b
	v_mov_b32_e32 v165, 0xbfb8aa3b
	v_lshl_or_b32 v148, s68, 7, v145
	v_lshl_add_u32 v147, s90, 8, v3
	v_ashrrev_i32_e32 v149, 31, v148
	v_mov_b64_e32 v[142:143], s[16:17]
	s_andn2_b64 vcc, exec, s[4:5]
	v_mad_i64_i32 v[150:151], s[42:43], v147, s40, v[142:143]
	s_nop 0
	v_pk_mul_f32 v[156:157], v[128:129], v[164:165]
	v_pk_mul_f32 v[158:159], v[130:131], v[164:165]
	v_pk_mul_f32 v[160:161], v[120:121], v[164:165]
	v_pk_mul_f32 v[162:163], v[122:123], v[164:165]
	v_exp_f32_e32 v156, v156
	v_exp_f32_e32 v157, v157
	v_exp_f32_e32 v158, v158
	v_exp_f32_e32 v159, v159
	v_exp_f32_e32 v160, v160
	v_exp_f32_e32 v161, v161
	v_exp_f32_e32 v162, v162
	v_exp_f32_e32 v163, v163
	v_pk_add_f32 v[156:157], v[156:157], 1.0 op_sel_hi:[1,0]
	v_pk_add_f32 v[158:159], v[158:159], 1.0 op_sel_hi:[1,0]
	v_pk_add_f32 v[160:161], v[160:161], 1.0 op_sel_hi:[1,0]
	v_pk_add_f32 v[162:163], v[162:163], 1.0 op_sel_hi:[1,0]
	v_rcp_f32_e32 v156, v156
	v_rcp_f32_e32 v157, v157
	v_rcp_f32_e32 v158, v158
	v_rcp_f32_e32 v159, v159
	v_rcp_f32_e32 v160, v160
	v_rcp_f32_e32 v161, v161
	v_rcp_f32_e32 v162, v162
	v_rcp_f32_e32 v163, v163
	v_pk_mul_f32 v[156:157], v[128:129], v[156:157]
	v_pk_mul_f32 v[158:159], v[130:131], v[158:159]
	v_pk_mul_f32 v[160:161], v[120:121], v[160:161]
	v_pk_mul_f32 v[162:163], v[122:123], v[162:163]
	v_pk_mul_f32 v[124:125], v[156:157], v[124:125]
	v_pk_mul_f32 v[126:127], v[158:159], v[126:127]
	v_pk_mul_f32 v[120:121], v[160:161], v[116:117]
	v_pk_mul_f32 v[128:129], v[162:163], v[118:119]
	v_cvt_pk_bf16_f32 v118, v124, v125
	v_lshlrev_b64 v[116:117], 1, v[148:149]
	v_lshl_add_u64 v[122:123], v[150:151], 0, v[116:117]
	v_cvt_pk_bf16_f32 v119, v126, v127
	v_cvt_pk_bf16_f32 v120, v120, v121
	v_cvt_pk_bf16_f32 v121, v128, v129
	global_store_dwordx4 v[122:123], v[118:121], off
	s_nop 1
	v_add_u32_e32 v118, 16, v147
	v_mad_i64_i32 v[118:119], s[42:43], v118, s40, v[142:143]
	v_pk_mul_f32 v[156:157], v[112:113], v[164:165]
	v_pk_mul_f32 v[158:159], v[114:115], v[164:165]
	v_pk_mul_f32 v[160:161], v[104:105], v[164:165]
	v_pk_mul_f32 v[162:163], v[106:107], v[164:165]
	v_exp_f32_e32 v156, v156
	v_exp_f32_e32 v157, v157
	v_exp_f32_e32 v158, v158
	v_exp_f32_e32 v159, v159
	v_exp_f32_e32 v160, v160
	v_exp_f32_e32 v161, v161
	v_exp_f32_e32 v162, v162
	v_exp_f32_e32 v163, v163
	v_pk_add_f32 v[156:157], v[156:157], 1.0 op_sel_hi:[1,0]
	v_pk_add_f32 v[158:159], v[158:159], 1.0 op_sel_hi:[1,0]
	v_pk_add_f32 v[160:161], v[160:161], 1.0 op_sel_hi:[1,0]
	v_pk_add_f32 v[162:163], v[162:163], 1.0 op_sel_hi:[1,0]
	v_rcp_f32_e32 v156, v156
	v_rcp_f32_e32 v157, v157
	v_rcp_f32_e32 v158, v158
	v_rcp_f32_e32 v159, v159
	v_rcp_f32_e32 v160, v160
	v_rcp_f32_e32 v161, v161
	v_rcp_f32_e32 v162, v162
	v_rcp_f32_e32 v163, v163
	v_pk_mul_f32 v[156:157], v[112:113], v[156:157]
	v_pk_mul_f32 v[158:159], v[114:115], v[158:159]
	v_pk_mul_f32 v[160:161], v[104:105], v[160:161]
	v_pk_mul_f32 v[162:163], v[106:107], v[162:163]
	v_pk_mul_f32 v[108:109], v[156:157], v[108:109]
	v_pk_mul_f32 v[110:111], v[158:159], v[110:111]
	v_pk_mul_f32 v[112:113], v[160:161], v[100:101]
	v_mul_f32_e32 v106, v162, v102
	v_mul_f32_e32 v103, v163, v103
	v_lshl_add_u64 v[104:105], v[118:119], 0, v[116:117]
	v_cvt_pk_bf16_f32 v100, v108, v109
	v_cvt_pk_bf16_f32 v101, v110, v111
	v_cvt_pk_bf16_f32 v102, v112, v113
	v_cvt_pk_bf16_f32 v103, v106, v103
	global_store_dwordx4 v[104:105], v[100:103], off
	s_nop 1
	v_add_u32_e32 v100, 32, v147
	v_mad_i64_i32 v[100:101], s[42:43], v100, s40, v[142:143]
	v_pk_mul_f32 v[156:157], v[96:97], v[164:165]
	v_pk_mul_f32 v[158:159], v[98:99], v[164:165]
	v_pk_mul_f32 v[160:161], v[88:89], v[164:165]
	v_pk_mul_f32 v[162:163], v[90:91], v[164:165]
	v_exp_f32_e32 v156, v156
	v_exp_f32_e32 v157, v157
	v_exp_f32_e32 v158, v158
	v_exp_f32_e32 v159, v159
	v_exp_f32_e32 v160, v160
	v_exp_f32_e32 v161, v161
	v_exp_f32_e32 v162, v162
	v_exp_f32_e32 v163, v163
	v_pk_add_f32 v[156:157], v[156:157], 1.0 op_sel_hi:[1,0]
	v_pk_add_f32 v[158:159], v[158:159], 1.0 op_sel_hi:[1,0]
	v_pk_add_f32 v[160:161], v[160:161], 1.0 op_sel_hi:[1,0]
	v_pk_add_f32 v[162:163], v[162:163], 1.0 op_sel_hi:[1,0]
	v_rcp_f32_e32 v156, v156
	v_rcp_f32_e32 v157, v157
	v_rcp_f32_e32 v158, v158
	v_rcp_f32_e32 v159, v159
	v_rcp_f32_e32 v160, v160
	v_rcp_f32_e32 v161, v161
	v_rcp_f32_e32 v162, v162
	v_rcp_f32_e32 v163, v163
	v_pk_mul_f32 v[156:157], v[96:97], v[156:157]
	v_pk_mul_f32 v[158:159], v[98:99], v[158:159]
	v_pk_mul_f32 v[160:161], v[88:89], v[160:161]
	v_pk_mul_f32 v[162:163], v[90:91], v[162:163]
	v_pk_mul_f32 v[92:93], v[156:157], v[92:93]
	v_pk_mul_f32 v[94:95], v[158:159], v[94:95]
	v_pk_mul_f32 v[96:97], v[160:161], v[84:85]
	v_mul_f32_e32 v90, v162, v86
	v_mul_f32_e32 v87, v163, v87
	v_lshl_add_u64 v[88:89], v[100:101], 0, v[116:117]
	v_cvt_pk_bf16_f32 v84, v92, v93
	v_cvt_pk_bf16_f32 v85, v94, v95
	v_cvt_pk_bf16_f32 v86, v96, v97
	v_cvt_pk_bf16_f32 v87, v90, v87
	global_store_dwordx4 v[88:89], v[84:87], off
	s_nop 1
	v_add_u32_e32 v84, 48, v147
	v_mad_i64_i32 v[84:85], s[42:43], v84, s40, v[142:143]
	v_pk_mul_f32 v[156:157], v[80:81], v[164:165]
	v_pk_mul_f32 v[158:159], v[82:83], v[164:165]
	v_pk_mul_f32 v[160:161], v[72:73], v[164:165]
	v_pk_mul_f32 v[162:163], v[74:75], v[164:165]
	v_exp_f32_e32 v156, v156
	v_exp_f32_e32 v157, v157
	v_exp_f32_e32 v158, v158
	v_exp_f32_e32 v159, v159
	v_exp_f32_e32 v160, v160
	v_exp_f32_e32 v161, v161
	v_exp_f32_e32 v162, v162
	v_exp_f32_e32 v163, v163
	v_pk_add_f32 v[156:157], v[156:157], 1.0 op_sel_hi:[1,0]
	v_pk_add_f32 v[158:159], v[158:159], 1.0 op_sel_hi:[1,0]
	v_pk_add_f32 v[160:161], v[160:161], 1.0 op_sel_hi:[1,0]
; __device__ __forceinline__ unsigned cvt_pk_bf16(float lo, float hi) { unsigned r; asm volatile("v_cvt_pk_bf16_f32 %0, %1, %2" : "=v"(r) : "v"(lo), "v"(hi)); return r; }
;     __device__ __forceinline__ void operator()(const f32x4 (&acc)[2][2][4][2], const Unit& u, int wr, int wc, int fr, int fq) const {
;     ...
;             for (int m = 0; m < 4; ++m) { bf16_t* rowp = T + (size_t)(row0 + ai * HALF + m * 16) * ldc + col0; float t[8];
; #pragma unroll
;                 for (int n = 0; n < 2; ++n) { const f32x4 a = acc[ai][0][m][n], b = acc[ai][1][m][n];
; #pragma unroll
;                     for (int e = 0; e < 4; ++e) t[4 * n + e] = a[e] * __builtin_amdgcn_rcpf(1.0f + __expf(-a[e])) * b[e]; }
;                 u32x4 w; w.x = cvt_pk_bf16(t[0], t[1]); w.y = cvt_pk_bf16(t[2], t[3]); w.z = cvt_pk_bf16(t[4], t[5]); w.w = cvt_pk_bf16(t[6], t[7]);
;                 *(u32x4*)rowp = w; }
	v_pk_add_f32 v[162:163], v[162:163], 1.0 op_sel_hi:[1,0]
	v_rcp_f32_e32 v156, v156
	v_rcp_f32_e32 v157, v157
	v_rcp_f32_e32 v158, v158
	v_rcp_f32_e32 v159, v159
	v_rcp_f32_e32 v160, v160
	v_rcp_f32_e32 v161, v161
	v_rcp_f32_e32 v162, v162
	v_rcp_f32_e32 v163, v163
	v_pk_mul_f32 v[156:157], v[80:81], v[156:157]
	v_pk_mul_f32 v[158:159], v[82:83], v[158:159]
	v_pk_mul_f32 v[160:161], v[72:73], v[160:161]
	v_pk_mul_f32 v[162:163], v[74:75], v[162:163]
	v_pk_mul_f32 v[76:77], v[156:157], v[76:77]
	v_pk_mul_f32 v[78:79], v[158:159], v[78:79]
	v_pk_mul_f32 v[80:81], v[160:161], v[68:69]
	v_mul_f32_e32 v74, v162, v70
	v_mul_f32_e32 v71, v163, v71
	v_lshl_add_u64 v[72:73], v[84:85], 0, v[116:117]
	v_cvt_pk_bf16_f32 v68, v76, v77
	v_cvt_pk_bf16_f32 v69, v78, v79
	v_cvt_pk_bf16_f32 v70, v80, v81
	v_cvt_pk_bf16_f32 v71, v74, v71
	global_store_dwordx4 v[72:73], v[68:71], off
	s_nop 1
	v_add_u32_e32 v68, 0x80, v147
	v_mad_i64_i32 v[68:69], s[42:43], v68, s40, v[142:143]
	v_pk_mul_f32 v[156:157], v[64:65], v[164:165]
	v_pk_mul_f32 v[158:159], v[66:67], v[164:165]
	v_pk_mul_f32 v[160:161], v[56:57], v[164:165]
	v_pk_mul_f32 v[162:163], v[58:59], v[164:165]
	v_exp_f32_e32 v156, v156
	v_exp_f32_e32 v157, v157
	v_exp_f32_e32 v158, v158
	v_exp_f32_e32 v159, v159
	v_exp_f32_e32 v160, v160
	v_exp_f32_e32 v161, v161
	v_exp_f32_e32 v162, v162
	v_exp_f32_e32 v163, v163
	v_pk_add_f32 v[156:157], v[156:157], 1.0 op_sel_hi:[1,0]
	v_pk_add_f32 v[158:159], v[158:159], 1.0 op_sel_hi:[1,0]
	v_pk_add_f32 v[160:161], v[160:161], 1.0 op_sel_hi:[1,0]
	v_pk_add_f32 v[162:163], v[162:163], 1.0 op_sel_hi:[1,0]
	v_rcp_f32_e32 v156, v156
	v_rcp_f32_e32 v157, v157
	v_rcp_f32_e32 v158, v158
	v_rcp_f32_e32 v159, v159
	v_rcp_f32_e32 v160, v160
	v_rcp_f32_e32 v161, v161
	v_rcp_f32_e32 v162, v162
	v_rcp_f32_e32 v163, v163
	v_pk_mul_f32 v[156:157], v[64:65], v[156:157]
	v_pk_mul_f32 v[158:159], v[66:67], v[158:159]
	v_pk_mul_f32 v[160:161], v[56:57], v[160:161]
	v_pk_mul_f32 v[162:163], v[58:59], v[162:163]
	v_pk_mul_f32 v[60:61], v[156:157], v[60:61]
	v_pk_mul_f32 v[62:63], v[158:159], v[62:63]
	v_pk_mul_f32 v[64:65], v[160:161], v[52:53]
	v_mul_f32_e32 v58, v162, v54
	v_mul_f32_e32 v55, v163, v55
	v_lshl_add_u64 v[56:57], v[68:69], 0, v[116:117]
	v_cvt_pk_bf16_f32 v52, v60, v61
	v_cvt_pk_bf16_f32 v53, v62, v63
	v_cvt_pk_bf16_f32 v54, v64, v65
	v_cvt_pk_bf16_f32 v55, v58, v55
	global_store_dwordx4 v[56:57], v[52:55], off
	s_nop 1
	v_add_u32_e32 v52, 0x90, v147
	v_mad_i64_i32 v[52:53], s[42:43], v52, s40, v[142:143]
	v_pk_mul_f32 v[156:157], v[48:49], v[164:165]
	v_pk_mul_f32 v[158:159], v[50:51], v[164:165]
	v_pk_mul_f32 v[160:161], v[40:41], v[164:165]
	v_pk_mul_f32 v[162:163], v[42:43], v[164:165]
	v_exp_f32_e32 v156, v156
	v_exp_f32_e32 v157, v157
	v_exp_f32_e32 v158, v158
	v_exp_f32_e32 v159, v159
	v_exp_f32_e32 v160, v160
	v_exp_f32_e32 v161, v161
	v_exp_f32_e32 v162, v162
	v_exp_f32_e32 v163, v163
	v_pk_add_f32 v[156:157], v[156:157], 1.0 op_sel_hi:[1,0]
	v_pk_add_f32 v[158:159], v[158:159], 1.0 op_sel_hi:[1,0]
	v_pk_add_f32 v[160:161], v[160:161], 1.0 op_sel_hi:[1,0]
	v_pk_add_f32 v[162:163], v[162:163], 1.0 op_sel_hi:[1,0]
	v_rcp_f32_e32 v156, v156
	v_rcp_f32_e32 v157, v157
	v_rcp_f32_e32 v158, v158
	v_rcp_f32_e32 v159, v159
	v_rcp_f32_e32 v160, v160
	v_rcp_f32_e32 v161, v161
	v_rcp_f32_e32 v162, v162
	v_rcp_f32_e32 v163, v163
	v_pk_mul_f32 v[156:157], v[48:49], v[156:157]
	v_pk_mul_f32 v[158:159], v[50:51], v[158:159]
	v_pk_mul_f32 v[160:161], v[40:41], v[160:161]
	v_pk_mul_f32 v[162:163], v[42:43], v[162:163]
	v_pk_mul_f32 v[44:45], v[156:157], v[44:45]
; __device__ __forceinline__ unsigned cvt_pk_bf16(float lo, float hi) { unsigned r; asm volatile("v_cvt_pk_bf16_f32 %0, %1, %2" : "=v"(r) : "v"(lo), "v"(hi)); return r; }
;     __device__ __forceinline__ void operator()(const f32x4 (&acc)[2][2][4][2], const Unit& u, int wr, int wc, int fr, int fq) const {
;     ...
;             for (int m = 0; m < 4; ++m) { bf16_t* rowp = T + (size_t)(row0 + ai * HALF + m * 16) * ldc + col0; float t[8];
; #pragma unroll
;                 for (int n = 0; n < 2; ++n) { const f32x4 a = acc[ai][0][m][n], b = acc[ai][1][m][n];
; #pragma unroll
;                     for (int e = 0; e < 4; ++e) t[4 * n + e] = a[e] * __builtin_amdgcn_rcpf(1.0f + __expf(-a[e])) * b[e]; }
;                 u32x4 w; w.x = cvt_pk_bf16(t[0], t[1]); w.y = cvt_pk_bf16(t[2], t[3]); w.z = cvt_pk_bf16(t[4], t[5]); w.w = cvt_pk_bf16(t[6], t[7]);
;                 *(u32x4*)rowp = w; }
	v_pk_mul_f32 v[46:47], v[158:159], v[46:47]
	v_pk_mul_f32 v[48:49], v[160:161], v[36:37]
	v_mul_f32_e32 v42, v162, v38
	v_mul_f32_e32 v39, v163, v39
	v_lshl_add_u64 v[40:41], v[52:53], 0, v[116:117]
	v_cvt_pk_bf16_f32 v36, v44, v45
	v_cvt_pk_bf16_f32 v37, v46, v47
	v_cvt_pk_bf16_f32 v38, v48, v49
	v_cvt_pk_bf16_f32 v39, v42, v39
	global_store_dwordx4 v[40:41], v[36:39], off
	s_nop 1
	v_add_u32_e32 v36, 0xa0, v147
	v_mad_i64_i32 v[36:37], s[42:43], v36, s40, v[142:143]
	v_pk_mul_f32 v[156:157], v[32:33], v[164:165]
	v_pk_mul_f32 v[158:159], v[34:35], v[164:165]
	v_pk_mul_f32 v[160:161], v[24:25], v[164:165]
	v_pk_mul_f32 v[162:163], v[26:27], v[164:165]
	v_exp_f32_e32 v156, v156
	v_exp_f32_e32 v157, v157
	v_exp_f32_e32 v158, v158
	v_exp_f32_e32 v159, v159
	v_exp_f32_e32 v160, v160
	v_exp_f32_e32 v161, v161
	v_exp_f32_e32 v162, v162
	v_exp_f32_e32 v163, v163
	v_pk_add_f32 v[156:157], v[156:157], 1.0 op_sel_hi:[1,0]
	v_pk_add_f32 v[158:159], v[158:159], 1.0 op_sel_hi:[1,0]
	v_pk_add_f32 v[160:161], v[160:161], 1.0 op_sel_hi:[1,0]
	v_pk_add_f32 v[162:163], v[162:163], 1.0 op_sel_hi:[1,0]
	v_rcp_f32_e32 v156, v156
	v_rcp_f32_e32 v157, v157
	v_rcp_f32_e32 v158, v158
	v_rcp_f32_e32 v159, v159
	v_rcp_f32_e32 v160, v160
	v_rcp_f32_e32 v161, v161
	v_rcp_f32_e32 v162, v162
	v_rcp_f32_e32 v163, v163
	v_pk_mul_f32 v[156:157], v[32:33], v[156:157]
	v_pk_mul_f32 v[158:159], v[34:35], v[158:159]
	v_pk_mul_f32 v[160:161], v[24:25], v[160:161]
	v_pk_mul_f32 v[162:163], v[26:27], v[162:163]
	v_pk_mul_f32 v[28:29], v[156:157], v[28:29]
	v_pk_mul_f32 v[30:31], v[158:159], v[30:31]
	v_pk_mul_f32 v[32:33], v[160:161], v[20:21]
	v_mul_f32_e32 v26, v162, v22
	v_mul_f32_e32 v23, v163, v23
	v_lshl_add_u64 v[24:25], v[36:37], 0, v[116:117]
	v_cvt_pk_bf16_f32 v20, v28, v29
	v_cvt_pk_bf16_f32 v21, v30, v31
	v_cvt_pk_bf16_f32 v22, v32, v33
	v_cvt_pk_bf16_f32 v23, v26, v23
	global_store_dwordx4 v[24:25], v[20:23], off
	s_nop 1
	v_add_u32_e32 v20, 0xb0, v147
	v_mad_i64_i32 v[20:21], s[42:43], v20, s40, v[142:143]
	s_mov_b64 s[42:43], -1
	v_pk_mul_f32 v[156:157], v[16:17], v[164:165]
	v_pk_mul_f32 v[158:159], v[18:19], v[164:165]
	v_pk_mul_f32 v[160:161], v[8:9], v[164:165]
	v_pk_mul_f32 v[162:163], v[10:11], v[164:165]
	v_exp_f32_e32 v156, v156
	v_exp_f32_e32 v157, v157
	v_exp_f32_e32 v158, v158
	v_exp_f32_e32 v159, v159
	v_exp_f32_e32 v160, v160
	v_exp_f32_e32 v161, v161
	v_exp_f32_e32 v162, v162
	v_exp_f32_e32 v163, v163
	v_pk_add_f32 v[156:157], v[156:157], 1.0 op_sel_hi:[1,0]
	v_pk_add_f32 v[158:159], v[158:159], 1.0 op_sel_hi:[1,0]
	v_pk_add_f32 v[160:161], v[160:161], 1.0 op_sel_hi:[1,0]
	v_pk_add_f32 v[162:163], v[162:163], 1.0 op_sel_hi:[1,0]
	v_rcp_f32_e32 v156, v156
	v_rcp_f32_e32 v157, v157
	v_rcp_f32_e32 v158, v158
	v_rcp_f32_e32 v159, v159
	v_rcp_f32_e32 v160, v160
	v_rcp_f32_e32 v161, v161
	v_rcp_f32_e32 v162, v162
	v_rcp_f32_e32 v163, v163
	v_pk_mul_f32 v[156:157], v[16:17], v[156:157]
	v_pk_mul_f32 v[158:159], v[18:19], v[158:159]
	v_pk_mul_f32 v[160:161], v[8:9], v[160:161]
	v_pk_mul_f32 v[162:163], v[10:11], v[162:163]
	v_pk_mul_f32 v[12:13], v[156:157], v[12:13]
	v_pk_mul_f32 v[14:15], v[158:159], v[14:15]
	v_pk_mul_f32 v[16:17], v[160:161], v[4:5]
	v_mul_f32_e32 v10, v162, v6
	v_mul_f32_e32 v7, v163, v7
	v_lshl_add_u64 v[8:9], v[20:21], 0, v[116:117]
	v_cvt_pk_bf16_f32 v4, v12, v13
	v_cvt_pk_bf16_f32 v5, v14, v15
	v_cvt_pk_bf16_f32 v6, v16, v17
	v_cvt_pk_bf16_f32 v7, v10, v7
	global_store_dwordx4 v[8:9], v[4:7], off
	s_cbranch_vccnz .LBB0_333
	s_andn2_b64 vcc, exec, s[6:7]
	s_cbranch_vccnz .LBB0_332
	s_barrier
	s_branch .LBB0_332

; #define LAS __attribute__((address_space(3)))
; #define LDS_WAIT() asm volatile("s_waitcnt lgkmcnt(0)" ::: "memory")
; __device__ __forceinline__ void stage_z(const bf16_t* U, int tok0, int stride, int col_r, int col_i, LAS unsigned char* tile, int lane) {
;     ...
;     for (int it = 0; it < 16; ++it) { const int idx = it * 64 + lane, row = idx >> 3, piece = (idx >> 2) & 1, chunk = idx & 3;
;         v[it] = *(const u32x4*)(U + (size_t)(tok0 + stride * row) * NU + (piece ? col_i : col_r) + 8 * chunk); }
; #pragma unroll
;     for (int it = 0; it < 16; ++it) { const int idx = it * 64 + lane, row = idx >> 3, piece = (idx >> 2) & 1, chunk = idx & 3;
;         *(LAS u32x4*)(tile + row * 128 + ((piece ^ ((row >> 1) & 1)) * 64) + chunk * 16) = v[it]; }
; __device__ __forceinline__ void dftc_mfma(const bf16_t* U, bf16_t* Y, const bf16_t* A3, LAS unsigned char* tile, int gw, int NGW, int lane) {
;     ...
;         for (int pass = 0; pass < 2; ++pass) {
;             stage_z(U, ML + b * CTXL + 128 * pass, 1, UC_Z + 128 * g + 32 * nh, UC_Z + 128 * g + 64 + 32 * nh, tile, lane);
;             LDS_WAIT();
; #pragma unroll
;             for (int mb = 0; mb < 2; ++mb) { const bf16_t* ap = A3 + (size_t)(64 * oq + 32 * mb + r32) * 512 + 128 * pass + 8 * hh;
; #pragma unroll
;                 for (int kk = 0; kk < 8; ++kk) { const bf16x8 ac = *(const bf16x8*)(ap + 16 * kk), as = *(const bf16x8*)(ap + 256 + 16 * kk);
;                     const bf16x8 br = tr2(tile + offR + kk * 2048, 512), bi = tr2(tile + offI + kk * 2048, 512);
;                     acc[mb] = __builtin_amdgcn_mfma_f32_32x32x16_bf16(ac, br, acc[mb], 0, 0, 0); acc[mb] = __builtin_amdgcn_mfma_f32_32x32x16_bf16(as, bi, acc[mb], 0, 0, 0); } }
.LBB0_532:
	s_lshl_b32 s1, s6, 4
	s_and_b32 s1, s1, 0x180
	s_and_b32 s3, s7, 32
	v_add_u32_e32 v4, s1, v48
	s_and_b32 s8, s7, 0xffffff00
	v_or_b32_e32 v4, s3, v4
	s_add_i32 s0, s8, 0x8000
	v_lshlrev_b32_e32 v4, 1, v4
	v_mov_b32_e32 v5, v2
	v_lshl_add_u64 v[114:115], v[0:1], 0, v[4:5]
	v_or_b32_e32 v43, s0, v3
	v_mad_i64_i32 v[4:5], s[4:5], v43, s50, v[114:115]
	v_or_b32_e32 v8, 8, v43
	global_load_dwordx4 v[4:7], v[4:5], off
	v_mad_i64_i32 v[8:9], s[4:5], v8, s50, v[114:115]
	v_or_b32_e32 v12, 16, v43
	global_load_dwordx4 v[8:11], v[8:9], off
	v_mad_i64_i32 v[12:13], s[4:5], v12, s50, v[114:115]
	v_or_b32_e32 v16, 24, v43
	global_load_dwordx4 v[12:15], v[12:13], off
	v_mad_i64_i32 v[16:17], s[4:5], v16, s50, v[114:115]
	v_or_b32_e32 v20, 32, v43
	global_load_dwordx4 v[16:19], v[16:17], off
	v_mad_i64_i32 v[20:21], s[4:5], v20, s50, v[114:115]
	v_or_b32_e32 v24, 40, v43
	global_load_dwordx4 v[20:23], v[20:21], off
	v_mad_i64_i32 v[24:25], s[4:5], v24, s50, v[114:115]
	v_or_b32_e32 v28, 48, v43
	global_load_dwordx4 v[24:27], v[24:25], off
	v_mad_i64_i32 v[28:29], s[4:5], v28, s50, v[114:115]
	v_or_b32_e32 v32, 56, v43
	global_load_dwordx4 v[28:31], v[28:29], off
	v_mad_i64_i32 v[32:33], s[4:5], v32, s50, v[114:115]
	v_or_b32_e32 v44, 64, v43
	global_load_dwordx4 v[32:35], v[32:33], off
	v_mad_i64_i32 v[44:45], s[4:5], v44, s50, v[114:115]
	v_or_b32_e32 v54, 0x48, v43
	global_load_dwordx4 v[44:47], v[44:45], off
	v_mad_i64_i32 v[54:55], s[4:5], v54, s50, v[114:115]
	v_or_b32_e32 v58, 0x50, v43
	global_load_dwordx4 v[54:57], v[54:55], off
	v_mad_i64_i32 v[58:59], s[4:5], v58, s50, v[114:115]
	v_or_b32_e32 v62, 0x58, v43
	global_load_dwordx4 v[58:61], v[58:59], off
	v_mad_i64_i32 v[62:63], s[4:5], v62, s50, v[114:115]
	v_or_b32_e32 v66, 0x60, v43
	global_load_dwordx4 v[62:65], v[62:63], off
	v_mad_i64_i32 v[66:67], s[4:5], v66, s50, v[114:115]
	v_or_b32_e32 v70, 0x68, v43
	global_load_dwordx4 v[66:69], v[66:67], off
	v_mad_i64_i32 v[70:71], s[4:5], v70, s50, v[114:115]
	v_or_b32_e32 v74, 0x70, v43
	global_load_dwordx4 v[70:73], v[70:71], off
	v_mad_i64_i32 v[74:75], s[4:5], v74, s50, v[114:115]
	v_or_b32_e32 v43, 0x78, v43
	global_load_dwordx4 v[74:77], v[74:75], off
	v_mad_i64_i32 v[78:79], s[4:5], v43, s50, v[114:115]
	global_load_dwordx4 v[78:81], v[78:79], off
	v_add_u32_e32 v43, s8, v49
	s_add_u32 s1, s18, s1
	global_load_dwordx4 v[136:139], v[36:37], off
	global_load_dwordx4 v[140:143], v[36:37], off offset:512
	global_load_dwordx4 v[144:147], v[36:37], off offset:32
	global_load_dwordx4 v[148:151], v[36:37], off offset:544
	global_load_dwordx4 v[152:155], v[36:37], off offset:64
	global_load_dwordx4 v[156:159], v[36:37], off offset:576
	global_load_dwordx4 v[160:163], v[36:37], off offset:96
	global_load_dwordx4 v[164:167], v[36:37], off offset:608
	global_load_dwordx4 v[168:171], v[36:37], off offset:128
	global_load_dwordx4 v[172:175], v[36:37], off offset:640
	global_load_dwordx4 v[176:179], v[36:37], off offset:160
	global_load_dwordx4 v[180:183], v[36:37], off offset:672
	global_load_dwordx4 v[188:191], v[36:37], off offset:192
	global_load_dwordx4 v[192:195], v[36:37], off offset:704
	global_load_dwordx4 v[196:199], v[36:37], off offset:224
	global_load_dwordx4 v[200:203], v[36:37], off offset:736
	s_waitcnt vmcnt(0) lgkmcnt(0)
	ds_write_b128 v51, v[4:7]
	ds_write_b128 v51, v[8:11] offset:1024
	ds_write_b128 v51, v[12:15] offset:2048
	ds_write_b128 v51, v[16:19] offset:3072
	ds_write_b128 v51, v[20:23] offset:4096
	ds_write_b128 v51, v[24:27] offset:5120
	ds_write_b128 v51, v[28:31] offset:6144
	ds_write_b128 v51, v[32:35] offset:7168
	ds_write_b128 v51, v[44:47] offset:8192
	ds_write_b128 v51, v[54:57] offset:9216
	ds_write_b128 v51, v[58:61] offset:10240
	ds_write_b128 v51, v[62:65] offset:11264
	ds_write_b128 v51, v[66:69] offset:12288
	ds_write_b128 v51, v[70:73] offset:13312
	ds_write_b128 v51, v[74:77] offset:14336
	ds_write_b128 v51, v[78:81] offset:15360
	s_waitcnt lgkmcnt(0)
	ds_read_b64_tr_b16 v[12:13], v52
	ds_read_b64_tr_b16 v[14:15], v52 offset:512
	ds_read_b64_tr_b16 v[44:45], v53
	ds_read_b64_tr_b16 v[46:47], v53 offset:512
	s_waitcnt vmcnt(0) lgkmcnt(0)
	v_mfma_f32_32x32x16_bf16 v[20:35], v[136:139], v[12:15], 0
	v_mfma_f32_32x32x16_bf16 v[20:35], v[140:143], v[44:47], v[20:35]
	ds_read_b64_tr_b16 v[54:55], v52 offset:2048
	ds_read_b64_tr_b16 v[56:57], v52 offset:2560
	ds_read_b64_tr_b16 v[58:59], v53 offset:2048
	ds_read_b64_tr_b16 v[60:61], v53 offset:2560
	s_waitcnt vmcnt(0) lgkmcnt(0)
	v_mfma_f32_32x32x16_bf16 v[20:35], v[144:147], v[54:57], v[20:35]
	v_mfma_f32_32x32x16_bf16 v[20:35], v[148:151], v[58:61], v[20:35]
	ds_read_b64_tr_b16 v[62:63], v52 offset:4096
	ds_read_b64_tr_b16 v[64:65], v52 offset:4608
	ds_read_b64_tr_b16 v[66:67], v53 offset:4096
	ds_read_b64_tr_b16 v[68:69], v53 offset:4608
	s_waitcnt vmcnt(0) lgkmcnt(0)
	v_mfma_f32_32x32x16_bf16 v[20:35], v[152:155], v[62:65], v[20:35]
	v_mfma_f32_32x32x16_bf16 v[20:35], v[156:159], v[66:69], v[20:35]
	ds_read_b64_tr_b16 v[70:71], v52 offset:6144
	ds_read_b64_tr_b16 v[72:73], v52 offset:6656
	ds_read_b64_tr_b16 v[74:75], v53 offset:6144
	ds_read_b64_tr_b16 v[76:77], v53 offset:6656
	s_waitcnt vmcnt(0) lgkmcnt(0)
	v_mfma_f32_32x32x16_bf16 v[20:35], v[160:163], v[70:73], v[20:35]
	v_mfma_f32_32x32x16_bf16 v[20:35], v[164:167], v[74:77], v[20:35]
	ds_read_b64_tr_b16 v[78:79], v52 offset:8192
	ds_read_b64_tr_b16 v[80:81], v52 offset:8704
	ds_read_b64_tr_b16 v[82:83], v53 offset:8192
	ds_read_b64_tr_b16 v[84:85], v53 offset:8704
	s_waitcnt vmcnt(0) lgkmcnt(0)
; __device__ __forceinline__ void stage_z(const bf16_t* U, int tok0, int stride, int col_r, int col_i, LAS unsigned char* tile, int lane) {
;     ...
;     for (int it = 0; it < 16; ++it) { const int idx = it * 64 + lane, row = idx >> 3, piece = (idx >> 2) & 1, chunk = idx & 3;
;         v[it] = *(const u32x4*)(U + (size_t)(tok0 + stride * row) * NU + (piece ? col_i : col_r) + 8 * chunk); }
; __device__ __forceinline__ void dftc_mfma(const bf16_t* U, bf16_t* Y, const bf16_t* A3, LAS unsigned char* tile, int gw, int NGW, int lane) {
;     ...
;             for (int mb = 0; mb < 2; ++mb) { const bf16_t* ap = A3 + (size_t)(64 * oq + 32 * mb + r32) * 512 + 128 * pass + 8 * hh;
; #pragma unroll
;                 for (int kk = 0; kk < 8; ++kk) { const bf16x8 ac = *(const bf16x8*)(ap + 16 * kk), as = *(const bf16x8*)(ap + 256 + 16 * kk);
;                     const bf16x8 br = tr2(tile + offR + kk * 2048, 512), bi = tr2(tile + offI + kk * 2048, 512);
;                     acc[mb] = __builtin_amdgcn_mfma_f32_32x32x16_bf16(ac, br, acc[mb], 0, 0, 0); acc[mb] = __builtin_amdgcn_mfma_f32_32x32x16_bf16(as, bi, acc[mb], 0, 0, 0); } }
	v_mfma_f32_32x32x16_bf16 v[20:35], v[168:171], v[78:81], v[20:35]
	v_mfma_f32_32x32x16_bf16 v[20:35], v[172:175], v[82:85], v[20:35]
	ds_read_b64_tr_b16 v[86:87], v52 offset:10240
	ds_read_b64_tr_b16 v[88:89], v52 offset:10752
	ds_read_b64_tr_b16 v[90:91], v53 offset:10240
	ds_read_b64_tr_b16 v[92:93], v53 offset:10752
	s_waitcnt vmcnt(0) lgkmcnt(0)
	v_mfma_f32_32x32x16_bf16 v[20:35], v[176:179], v[86:89], v[20:35]
	v_mfma_f32_32x32x16_bf16 v[20:35], v[180:183], v[90:93], v[20:35]
	ds_read_b64_tr_b16 v[94:95], v52 offset:12288
	ds_read_b64_tr_b16 v[96:97], v52 offset:12800
	ds_read_b64_tr_b16 v[98:99], v53 offset:12288
	ds_read_b64_tr_b16 v[100:101], v53 offset:12800
	s_waitcnt vmcnt(0) lgkmcnt(0)
	v_mfma_f32_32x32x16_bf16 v[20:35], v[188:191], v[94:97], v[20:35]
	v_mfma_f32_32x32x16_bf16 v[20:35], v[192:195], v[98:101], v[20:35]
	ds_read_b64_tr_b16 v[102:103], v52 offset:14336
	ds_read_b64_tr_b16 v[104:105], v52 offset:14848
	ds_read_b64_tr_b16 v[106:107], v53 offset:14336
	ds_read_b64_tr_b16 v[108:109], v53 offset:14848
	s_waitcnt vmcnt(0) lgkmcnt(0)
	v_mfma_f32_32x32x16_bf16 v[20:35], v[196:199], v[102:105], v[20:35]
	v_mfma_f32_32x32x16_bf16 v[20:35], v[200:203], v[106:109], v[20:35]
	global_load_dwordx4 v[136:139], v[38:39], off
	global_load_dwordx4 v[140:143], v[38:39], off offset:512
	global_load_dwordx4 v[144:147], v[38:39], off offset:32
	global_load_dwordx4 v[148:151], v[38:39], off offset:544
	global_load_dwordx4 v[152:155], v[38:39], off offset:64
	global_load_dwordx4 v[156:159], v[38:39], off offset:576
	global_load_dwordx4 v[160:163], v[38:39], off offset:96
	global_load_dwordx4 v[164:167], v[38:39], off offset:608
	global_load_dwordx4 v[168:171], v[38:39], off offset:128
	global_load_dwordx4 v[172:175], v[38:39], off offset:640
	global_load_dwordx4 v[176:179], v[38:39], off offset:160
	global_load_dwordx4 v[180:183], v[38:39], off offset:672
	global_load_dwordx4 v[188:191], v[38:39], off offset:192
	global_load_dwordx4 v[192:195], v[38:39], off offset:704
	global_load_dwordx4 v[196:199], v[38:39], off offset:224
	global_load_dwordx4 v[200:203], v[38:39], off offset:736
	s_waitcnt vmcnt(0) lgkmcnt(0)
	v_mfma_f32_32x32x16_bf16 v[4:19], v[136:139], v[12:15], 0
	v_mfma_f32_32x32x16_bf16 v[4:19], v[140:143], v[44:47], v[4:19]
	s_waitcnt vmcnt(0) lgkmcnt(0)
	v_mfma_f32_32x32x16_bf16 v[4:19], v[144:147], v[54:57], v[4:19]
	v_mfma_f32_32x32x16_bf16 v[4:19], v[148:151], v[58:61], v[4:19]
	v_or_b32_e32 v58, 16, v43
	v_mad_i64_i32 v[58:59], s[4:5], v58, s50, v[114:115]
	s_waitcnt vmcnt(0) lgkmcnt(0)
	v_mfma_f32_32x32x16_bf16 v[4:19], v[152:155], v[62:65], v[4:19]
	v_or_b32_e32 v62, 24, v43
	v_mad_i64_i32 v[62:63], s[4:5], v62, s50, v[114:115]
	v_mfma_f32_32x32x16_bf16 v[4:19], v[156:159], v[66:69], v[4:19]
	v_or_b32_e32 v66, 32, v43
	v_mad_i64_i32 v[66:67], s[4:5], v66, s50, v[114:115]
	s_waitcnt vmcnt(0) lgkmcnt(0)
	v_mfma_f32_32x32x16_bf16 v[4:19], v[160:163], v[70:73], v[4:19]
	v_or_b32_e32 v70, 40, v43
	v_mad_i64_i32 v[70:71], s[4:5], v70, s50, v[114:115]
	v_mfma_f32_32x32x16_bf16 v[4:19], v[164:167], v[74:77], v[4:19]
	v_or_b32_e32 v74, 48, v43
	v_mad_i64_i32 v[74:75], s[4:5], v74, s50, v[114:115]
	s_waitcnt vmcnt(0) lgkmcnt(0)
	v_mfma_f32_32x32x16_bf16 v[4:19], v[168:171], v[78:81], v[4:19]
	v_or_b32_e32 v78, 56, v43
	v_mad_i64_i32 v[78:79], s[4:5], v78, s50, v[114:115]
	v_mfma_f32_32x32x16_bf16 v[4:19], v[172:175], v[82:85], v[4:19]
	v_or_b32_e32 v82, 64, v43
	v_mad_i64_i32 v[82:83], s[4:5], v82, s50, v[114:115]
	s_waitcnt vmcnt(0) lgkmcnt(0)
	v_mfma_f32_32x32x16_bf16 v[4:19], v[176:179], v[86:89], v[4:19]
	v_or_b32_e32 v86, 0x48, v43
	v_mad_i64_i32 v[86:87], s[4:5], v86, s50, v[114:115]
	v_mfma_f32_32x32x16_bf16 v[4:19], v[180:183], v[90:93], v[4:19]
	v_or_b32_e32 v90, 0x50, v43
	v_mad_i64_i32 v[90:91], s[4:5], v90, s50, v[114:115]
	s_waitcnt vmcnt(0) lgkmcnt(0)
	v_mfma_f32_32x32x16_bf16 v[4:19], v[188:191], v[94:97], v[4:19]
	v_or_b32_e32 v94, 0x58, v43
	v_mad_i64_i32 v[94:95], s[4:5], v94, s50, v[114:115]
	v_mfma_f32_32x32x16_bf16 v[4:19], v[192:195], v[98:101], v[4:19]
	s_waitcnt lgkmcnt(0)
	global_load_dwordx4 v[58:61], v[58:59], off
	v_or_b32_e32 v98, 0x60, v43
	global_load_dwordx4 v[62:65], v[62:63], off
	v_mad_i64_i32 v[98:99], s[4:5], v98, s50, v[114:115]
	global_load_dwordx4 v[66:69], v[66:67], off
	s_waitcnt vmcnt(0) lgkmcnt(0)
	v_mfma_f32_32x32x16_bf16 v[4:19], v[196:199], v[102:105], v[4:19]
	v_mad_i64_i32 v[44:45], s[4:5], v43, s50, v[114:115]
	global_load_dwordx4 v[44:47], v[44:45], off
	v_or_b32_e32 v102, 0x68, v43
	global_load_dwordx4 v[70:73], v[70:71], off
	v_mad_i64_i32 v[102:103], s[4:5], v102, s50, v[114:115]
	v_mfma_f32_32x32x16_bf16 v[4:19], v[200:203], v[106:109], v[4:19]
	v_or_b32_e32 v54, 8, v43
	v_mad_i64_i32 v[54:55], s[4:5], v54, s50, v[114:115]
	global_load_dwordx4 v[54:57], v[54:55], off
	v_or_b32_e32 v106, 0x70, v43
	global_load_dwordx4 v[74:77], v[74:75], off
	v_mad_i64_i32 v[106:107], s[4:5], v106, s50, v[114:115]
	global_load_dwordx4 v[78:81], v[78:79], off
	v_or_b32_e32 v43, 0x78, v43
	global_load_dwordx4 v[82:85], v[82:83], off
	v_mad_i64_i32 v[110:111], s[4:5], v43, s50, v[114:115]
	global_load_dwordx4 v[86:89], v[86:87], off
	s_addc_u32 s5, s19, 0
	global_load_dwordx4 v[90:93], v[90:91], off
	s_lshl_b32 s3, s3, 1
	global_load_dwordx4 v[94:97], v[94:95], off
	s_add_u32 s4, s1, s3
	global_load_dwordx4 v[98:101], v[98:99], off
	s_addc_u32 s5, s5, 0
	global_load_dwordx4 v[102:105], v[102:103], off
	v_mov_b32_e32 v43, v2
	global_load_dwordx4 v[106:109], v[106:107], off
	s_add_i32 s6, s6, s12
	global_load_dwordx4 v[110:113], v[110:111], off
	global_load_dwordx4 v[136:139], v[36:37], off offset:256
	global_load_dwordx4 v[140:143], v[36:37], off offset:768
	global_load_dwordx4 v[144:147], v[36:37], off offset:288
	global_load_dwordx4 v[148:151], v[36:37], off offset:800
	global_load_dwordx4 v[152:155], v[36:37], off offset:320
	global_load_dwordx4 v[156:159], v[36:37], off offset:832
	global_load_dwordx4 v[160:163], v[36:37], off offset:352
	global_load_dwordx4 v[164:167], v[36:37], off offset:864
	global_load_dwordx4 v[168:171], v[36:37], off offset:384
	global_load_dwordx4 v[172:175], v[36:37], off offset:896
	global_load_dwordx4 v[176:179], v[36:37], off offset:416
	global_load_dwordx4 v[180:183], v[36:37], off offset:928
	global_load_dwordx4 v[188:191], v[36:37], off offset:448
	global_load_dwordx4 v[192:195], v[36:37], off offset:960
	global_load_dwordx4 v[196:199], v[36:37], off offset:480
	global_load_dwordx4 v[200:203], v[36:37], off offset:992
	s_waitcnt vmcnt(0) lgkmcnt(0)
; __device__ __forceinline__ bf16_t bf1(float v) { return (bf16_t)pk2(v, 0.f); }
; #define LDS_WAIT() asm volatile("s_waitcnt lgkmcnt(0)" ::: "memory")
; __device__ __forceinline__ void dftc_mfma(const bf16_t* U, bf16_t* Y, const bf16_t* A3, LAS unsigned char* tile, int gw, int NGW, int lane) {
;     ...
;         for (int pass = 0; pass < 2; ++pass) {
;             stage_z(U, ML + b * CTXL + 128 * pass, 1, UC_Z + 128 * g + 32 * nh, UC_Z + 128 * g + 64 + 32 * nh, tile, lane);
;             LDS_WAIT();
; #pragma unroll
;             for (int mb = 0; mb < 2; ++mb) { const bf16_t* ap = A3 + (size_t)(64 * oq + 32 * mb + r32) * 512 + 128 * pass + 8 * hh;
; #pragma unroll
;                 for (int kk = 0; kk < 8; ++kk) { const bf16x8 ac = *(const bf16x8*)(ap + 16 * kk), as = *(const bf16x8*)(ap + 256 + 16 * kk);
;                     const bf16x8 br = tr2(tile + offR + kk * 2048, 512), bi = tr2(tile + offI + kk * 2048, 512);
;                     acc[mb] = __builtin_amdgcn_mfma_f32_32x32x16_bf16(ac, br, acc[mb], 0, 0, 0); acc[mb] = __builtin_amdgcn_mfma_f32_32x32x16_bf16(as, bi, acc[mb], 0, 0, 0); } }
;             LDS_WAIT();
;         }
; #pragma unroll
;         for (int mb = 0; mb < 2; ++mb)
; #pragma unroll
;             for (int i = 0; i < 16; ++i) { const int k = 64 * oq + 32 * mb + 8 * (i >> 2) + 4 * hh + (i & 3);
;                 Y[(size_t)(ML + b * CTXL + k) * DM + 256 + 64 * g + 32 * nh + r32] = bf1(acc[mb][i] * (1.0f / 128.0f)); }
	ds_write_b128 v51, v[44:47]
	ds_write_b128 v51, v[54:57] offset:1024
	ds_write_b128 v51, v[58:61] offset:2048
	ds_write_b128 v51, v[62:65] offset:3072
	ds_write_b128 v51, v[66:69] offset:4096
	ds_write_b128 v51, v[70:73] offset:5120
	ds_write_b128 v51, v[74:77] offset:6144
	ds_write_b128 v51, v[78:81] offset:7168
	ds_write_b128 v51, v[82:85] offset:8192
	ds_write_b128 v51, v[86:89] offset:9216
	ds_write_b128 v51, v[90:93] offset:10240
	ds_write_b128 v51, v[94:97] offset:11264
	ds_write_b128 v51, v[98:101] offset:12288
	ds_write_b128 v51, v[102:105] offset:13312
	ds_write_b128 v51, v[106:109] offset:14336
	ds_write_b128 v51, v[110:113] offset:15360
	s_waitcnt lgkmcnt(0)
	ds_read_b64_tr_b16 v[58:59], v52
	ds_read_b64_tr_b16 v[60:61], v52 offset:512
	ds_read_b64_tr_b16 v[62:63], v53
	ds_read_b64_tr_b16 v[64:65], v53 offset:512
	s_add_i32 s7, s7, s11
	s_waitcnt vmcnt(0) lgkmcnt(0)
	v_mfma_f32_32x32x16_bf16 v[20:35], v[136:139], v[58:61], v[20:35]
	s_cmpk_gt_i32 s6, 0x7f
	v_mfma_f32_32x32x16_bf16 v[20:35], v[140:143], v[62:65], v[20:35]
	ds_read_b64_tr_b16 v[66:67], v52 offset:2048
	ds_read_b64_tr_b16 v[68:69], v52 offset:2560
	ds_read_b64_tr_b16 v[70:71], v53 offset:2048
	ds_read_b64_tr_b16 v[72:73], v53 offset:2560
	s_waitcnt vmcnt(0) lgkmcnt(0)
	v_mfma_f32_32x32x16_bf16 v[20:35], v[144:147], v[66:69], v[20:35]
	v_mfma_f32_32x32x16_bf16 v[20:35], v[148:151], v[70:73], v[20:35]
	ds_read_b64_tr_b16 v[74:75], v52 offset:4096
	ds_read_b64_tr_b16 v[76:77], v52 offset:4608
	ds_read_b64_tr_b16 v[78:79], v53 offset:4096
	ds_read_b64_tr_b16 v[80:81], v53 offset:4608
	s_waitcnt vmcnt(0) lgkmcnt(0)
	v_mfma_f32_32x32x16_bf16 v[20:35], v[152:155], v[74:77], v[20:35]
	v_mfma_f32_32x32x16_bf16 v[20:35], v[156:159], v[78:81], v[20:35]
	ds_read_b64_tr_b16 v[82:83], v52 offset:6144
	ds_read_b64_tr_b16 v[84:85], v52 offset:6656
	ds_read_b64_tr_b16 v[86:87], v53 offset:6144
	ds_read_b64_tr_b16 v[88:89], v53 offset:6656
	s_waitcnt vmcnt(0) lgkmcnt(0)
	v_mfma_f32_32x32x16_bf16 v[20:35], v[160:163], v[82:85], v[20:35]
	v_mfma_f32_32x32x16_bf16 v[20:35], v[164:167], v[86:89], v[20:35]
	ds_read_b64_tr_b16 v[90:91], v52 offset:8192
	ds_read_b64_tr_b16 v[92:93], v52 offset:8704
	ds_read_b64_tr_b16 v[94:95], v53 offset:8192
	ds_read_b64_tr_b16 v[96:97], v53 offset:8704
	s_waitcnt vmcnt(0) lgkmcnt(0)
	v_mfma_f32_32x32x16_bf16 v[20:35], v[168:171], v[90:93], v[20:35]
	v_mfma_f32_32x32x16_bf16 v[20:35], v[172:175], v[94:97], v[20:35]
	ds_read_b64_tr_b16 v[98:99], v52 offset:10240
	ds_read_b64_tr_b16 v[100:101], v52 offset:10752
	ds_read_b64_tr_b16 v[102:103], v53 offset:10240
	ds_read_b64_tr_b16 v[104:105], v53 offset:10752
	s_waitcnt vmcnt(0) lgkmcnt(0)
	v_mfma_f32_32x32x16_bf16 v[20:35], v[176:179], v[98:101], v[20:35]
	v_mfma_f32_32x32x16_bf16 v[20:35], v[180:183], v[102:105], v[20:35]
	ds_read_b64_tr_b16 v[106:107], v52 offset:12288
	ds_read_b64_tr_b16 v[108:109], v52 offset:12800
	ds_read_b64_tr_b16 v[110:111], v53 offset:12288
	ds_read_b64_tr_b16 v[112:113], v53 offset:12800
	s_waitcnt vmcnt(0) lgkmcnt(0)
	v_mfma_f32_32x32x16_bf16 v[20:35], v[188:191], v[106:109], v[20:35]
	v_mfma_f32_32x32x16_bf16 v[20:35], v[192:195], v[110:113], v[20:35]
	ds_read_b64_tr_b16 v[114:115], v52 offset:14336
	ds_read_b64_tr_b16 v[116:117], v52 offset:14848
	ds_read_b64_tr_b16 v[118:119], v53 offset:14336
	ds_read_b64_tr_b16 v[120:121], v53 offset:14848
	s_waitcnt vmcnt(0) lgkmcnt(0)
	v_mfma_f32_32x32x16_bf16 v[20:35], v[196:199], v[114:117], v[20:35]
	v_mfma_f32_32x32x16_bf16 v[20:35], v[200:203], v[118:121], v[20:35]
	global_load_dwordx4 v[136:139], v[40:41], off
	global_load_dwordx4 v[140:143], v[40:41], off offset:512
	global_load_dwordx4 v[144:147], v[40:41], off offset:32
	global_load_dwordx4 v[148:151], v[40:41], off offset:544
	global_load_dwordx4 v[152:155], v[40:41], off offset:64
	global_load_dwordx4 v[156:159], v[40:41], off offset:576
	global_load_dwordx4 v[160:163], v[40:41], off offset:96
	global_load_dwordx4 v[164:167], v[40:41], off offset:608
	global_load_dwordx4 v[168:171], v[40:41], off offset:128
	global_load_dwordx4 v[172:175], v[40:41], off offset:640
	global_load_dwordx4 v[176:179], v[40:41], off offset:160
	global_load_dwordx4 v[180:183], v[40:41], off offset:672
	global_load_dwordx4 v[188:191], v[40:41], off offset:192
	global_load_dwordx4 v[192:195], v[40:41], off offset:704
	global_load_dwordx4 v[196:199], v[40:41], off offset:224
	global_load_dwordx4 v[200:203], v[40:41], off offset:736
	s_waitcnt vmcnt(0) lgkmcnt(0)
	v_mfma_f32_32x32x16_bf16 v[4:19], v[136:139], v[58:61], v[4:19]
	s_nop 7
	v_mul_f32_e32 v20, 0x3c000000, v20
	v_cvt_pk_bf16_f32 v20, v20, s0
	v_mfma_f32_32x32x16_bf16 v[4:19], v[140:143], v[62:65], v[4:19]
	s_waitcnt vmcnt(0) lgkmcnt(0)
	v_mfma_f32_32x32x16_bf16 v[4:19], v[144:147], v[66:69], v[4:19]
	v_mfma_f32_32x32x16_bf16 v[4:19], v[148:151], v[70:73], v[4:19]
	s_waitcnt vmcnt(0) lgkmcnt(0)
	v_mfma_f32_32x32x16_bf16 v[4:19], v[152:155], v[74:77], v[4:19]
	v_mfma_f32_32x32x16_bf16 v[4:19], v[156:159], v[78:81], v[4:19]
	s_waitcnt vmcnt(0) lgkmcnt(0)
	v_mfma_f32_32x32x16_bf16 v[4:19], v[160:163], v[82:85], v[4:19]
	v_mfma_f32_32x32x16_bf16 v[4:19], v[164:167], v[86:89], v[4:19]
	s_waitcnt vmcnt(0) lgkmcnt(0)
	v_mfma_f32_32x32x16_bf16 v[4:19], v[168:171], v[90:93], v[4:19]
	v_mfma_f32_32x32x16_bf16 v[4:19], v[172:175], v[94:97], v[4:19]
	s_waitcnt vmcnt(0) lgkmcnt(0)
	v_mfma_f32_32x32x16_bf16 v[4:19], v[176:179], v[98:101], v[4:19]
	v_mfma_f32_32x32x16_bf16 v[4:19], v[180:183], v[102:105], v[4:19]
	s_waitcnt vmcnt(0) lgkmcnt(0)
	v_mfma_f32_32x32x16_bf16 v[4:19], v[188:191], v[106:109], v[4:19]
	v_mfma_f32_32x32x16_bf16 v[4:19], v[192:195], v[110:113], v[4:19]
	s_waitcnt lgkmcnt(0)
; __device__ __forceinline__ bf16_t bf1(float v) { return (bf16_t)pk2(v, 0.f); }
; #define LDS_WAIT() asm volatile("s_waitcnt lgkmcnt(0)" ::: "memory")
; __device__ __forceinline__ void dftc_mfma(const bf16_t* U, bf16_t* Y, const bf16_t* A3, LAS unsigned char* tile, int gw, int NGW, int lane) {
;     ...
;                     acc[mb] = __builtin_amdgcn_mfma_f32_32x32x16_bf16(ac, br, acc[mb], 0, 0, 0); acc[mb] = __builtin_amdgcn_mfma_f32_32x32x16_bf16(as, bi, acc[mb], 0, 0, 0); } }
;             LDS_WAIT();
;         }
; #pragma unroll
;         for (int mb = 0; mb < 2; ++mb)
; #pragma unroll
;             for (int i = 0; i < 16; ++i) { const int k = 64 * oq + 32 * mb + 8 * (i >> 2) + 4 * hh + (i & 3);
;                 Y[(size_t)(ML + b * CTXL + k) * DM + 256 + 64 * g + 32 * nh + r32] = bf1(acc[mb][i] * (1.0f / 128.0f)); }
	s_waitcnt vmcnt(0) lgkmcnt(0)
	v_mfma_f32_32x32x16_bf16 v[4:19], v[196:199], v[114:117], v[4:19]
	v_or_b32_e32 v46, s0, v50
	v_ashrrev_i32_e32 v47, 31, v46
	v_lshl_add_u64 v[44:45], s[4:5], 0, v[42:43]
	v_mfma_f32_32x32x16_bf16 v[4:19], v[200:203], v[118:121], v[4:19]
	v_lshlrev_b64 v[54:55], 11, v[46:47]
	v_lshl_add_u64 v[54:55], v[44:45], 0, v[54:55]
	global_store_short v[54:55], v20, off offset:512
	v_mul_f32_e32 v20, 0x3c000000, v21
	v_cvt_pk_bf16_f32 v43, v20, s0
	v_or_b32_e32 v20, 1, v46
	v_ashrrev_i32_e32 v21, 31, v20
	v_lshlrev_b64 v[20:21], 11, v[20:21]
	v_lshl_add_u64 v[20:21], v[44:45], 0, v[20:21]
	global_store_short v[20:21], v43, off offset:512
	v_mul_f32_e32 v20, 0x3c000000, v22
	v_cvt_pk_bf16_f32 v22, v20, s0
	v_or_b32_e32 v20, 2, v46
	v_ashrrev_i32_e32 v21, 31, v20
	v_lshlrev_b64 v[20:21], 11, v[20:21]
	v_lshl_add_u64 v[20:21], v[44:45], 0, v[20:21]
	global_store_short v[20:21], v22, off offset:512
	v_mul_f32_e32 v20, 0x3c000000, v23
	v_cvt_pk_bf16_f32 v22, v20, s0
	v_or_b32_e32 v20, 3, v46
	v_ashrrev_i32_e32 v21, 31, v20
	v_lshlrev_b64 v[20:21], 11, v[20:21]
	v_lshl_add_u64 v[20:21], v[44:45], 0, v[20:21]
	global_store_short v[20:21], v22, off offset:512
	v_mul_f32_e32 v20, 0x3c000000, v24
	v_cvt_pk_bf16_f32 v22, v20, s0
	v_or_b32_e32 v20, 8, v46
	v_ashrrev_i32_e32 v21, 31, v20
	v_lshlrev_b64 v[20:21], 11, v[20:21]
	v_lshl_add_u64 v[20:21], v[44:45], 0, v[20:21]
	global_store_short v[20:21], v22, off offset:512
	v_mul_f32_e32 v20, 0x3c000000, v25
	v_cvt_pk_bf16_f32 v22, v20, s0
	v_or_b32_e32 v20, 9, v46
	v_ashrrev_i32_e32 v21, 31, v20
	v_lshlrev_b64 v[20:21], 11, v[20:21]
	v_lshl_add_u64 v[20:21], v[44:45], 0, v[20:21]
	global_store_short v[20:21], v22, off offset:512
	v_mul_f32_e32 v20, 0x3c000000, v26
	v_cvt_pk_bf16_f32 v22, v20, s0
	v_or_b32_e32 v20, 10, v46
	v_ashrrev_i32_e32 v21, 31, v20
	v_lshlrev_b64 v[20:21], 11, v[20:21]
	v_lshl_add_u64 v[20:21], v[44:45], 0, v[20:21]
	global_store_short v[20:21], v22, off offset:512
	v_mul_f32_e32 v20, 0x3c000000, v27
	v_cvt_pk_bf16_f32 v22, v20, s0
	v_or_b32_e32 v20, 11, v46
	v_ashrrev_i32_e32 v21, 31, v20
	v_lshlrev_b64 v[20:21], 11, v[20:21]
	v_lshl_add_u64 v[20:21], v[44:45], 0, v[20:21]
	global_store_short v[20:21], v22, off offset:512
	v_mul_f32_e32 v20, 0x3c000000, v28
	v_cvt_pk_bf16_f32 v22, v20, s0
	v_or_b32_e32 v20, 16, v46
	v_ashrrev_i32_e32 v21, 31, v20
	v_lshlrev_b64 v[20:21], 11, v[20:21]
	v_lshl_add_u64 v[20:21], v[44:45], 0, v[20:21]
	global_store_short v[20:21], v22, off offset:512
	v_mul_f32_e32 v20, 0x3c000000, v29
	v_cvt_pk_bf16_f32 v22, v20, s0
	v_or_b32_e32 v20, 17, v46
	v_ashrrev_i32_e32 v21, 31, v20
	v_lshlrev_b64 v[20:21], 11, v[20:21]
	v_lshl_add_u64 v[20:21], v[44:45], 0, v[20:21]
	global_store_short v[20:21], v22, off offset:512
	v_mul_f32_e32 v20, 0x3c000000, v30
	v_cvt_pk_bf16_f32 v22, v20, s0
	v_or_b32_e32 v20, 18, v46
	v_ashrrev_i32_e32 v21, 31, v20
	v_lshlrev_b64 v[20:21], 11, v[20:21]
	v_lshl_add_u64 v[20:21], v[44:45], 0, v[20:21]
	global_store_short v[20:21], v22, off offset:512
	v_mul_f32_e32 v20, 0x3c000000, v31
	v_cvt_pk_bf16_f32 v22, v20, s0
	v_or_b32_e32 v20, 19, v46
	v_ashrrev_i32_e32 v21, 31, v20
	v_lshlrev_b64 v[20:21], 11, v[20:21]
	v_lshl_add_u64 v[20:21], v[44:45], 0, v[20:21]
	global_store_short v[20:21], v22, off offset:512
	v_mul_f32_e32 v20, 0x3c000000, v32
	v_cvt_pk_bf16_f32 v22, v20, s0
	v_or_b32_e32 v20, 24, v46
	v_ashrrev_i32_e32 v21, 31, v20
	v_lshlrev_b64 v[20:21], 11, v[20:21]
	v_lshl_add_u64 v[20:21], v[44:45], 0, v[20:21]
	global_store_short v[20:21], v22, off offset:512
	v_mul_f32_e32 v20, 0x3c000000, v33
	v_cvt_pk_bf16_f32 v22, v20, s0
	v_or_b32_e32 v20, 25, v46
	v_ashrrev_i32_e32 v21, 31, v20
	v_lshlrev_b64 v[20:21], 11, v[20:21]
	v_lshl_add_u64 v[20:21], v[44:45], 0, v[20:21]
	global_store_short v[20:21], v22, off offset:512
	v_mul_f32_e32 v20, 0x3c000000, v34
	v_cvt_pk_bf16_f32 v22, v20, s0
	v_or_b32_e32 v20, 26, v46
	v_ashrrev_i32_e32 v21, 31, v20
	v_lshlrev_b64 v[20:21], 11, v[20:21]
	v_lshl_add_u64 v[20:21], v[44:45], 0, v[20:21]
	global_store_short v[20:21], v22, off offset:512
	v_mul_f32_e32 v20, 0x3c000000, v35
	v_cvt_pk_bf16_f32 v22, v20, s0
; __device__ __forceinline__ bf16_t bf1(float v) { return (bf16_t)pk2(v, 0.f); }
; __device__ __forceinline__ void dftc_mfma(const bf16_t* U, bf16_t* Y, const bf16_t* A3, LAS unsigned char* tile, int gw, int NGW, int lane) {
;     ...
; #pragma unroll
;         for (int mb = 0; mb < 2; ++mb)
; #pragma unroll
;             for (int i = 0; i < 16; ++i) { const int k = 64 * oq + 32 * mb + 8 * (i >> 2) + 4 * hh + (i & 3);
;                 Y[(size_t)(ML + b * CTXL + k) * DM + 256 + 64 * g + 32 * nh + r32] = bf1(acc[mb][i] * (1.0f / 128.0f)); }
	v_or_b32_e32 v20, 27, v46
	v_ashrrev_i32_e32 v21, 31, v20
	v_lshlrev_b64 v[20:21], 11, v[20:21]
	v_lshl_add_u64 v[20:21], v[44:45], 0, v[20:21]
	global_store_short v[20:21], v22, off offset:512
	v_or_b32_e32 v20, 32, v46
	v_ashrrev_i32_e32 v21, 31, v20
	v_mul_f32_e32 v4, 0x3c000000, v4
	v_lshlrev_b64 v[20:21], 11, v[20:21]
	v_cvt_pk_bf16_f32 v4, v4, s0
	v_lshl_add_u64 v[20:21], v[44:45], 0, v[20:21]
	global_store_short v[20:21], v4, off offset:512
	v_mul_f32_e32 v4, 0x3c000000, v5
	v_cvt_pk_bf16_f32 v20, v4, s0
	v_or_b32_e32 v4, 33, v46
	v_ashrrev_i32_e32 v5, 31, v4
	v_lshlrev_b64 v[4:5], 11, v[4:5]
	v_lshl_add_u64 v[4:5], v[44:45], 0, v[4:5]
	global_store_short v[4:5], v20, off offset:512
	v_mul_f32_e32 v4, 0x3c000000, v6
	v_cvt_pk_bf16_f32 v6, v4, s0
	v_or_b32_e32 v4, 34, v46
	v_ashrrev_i32_e32 v5, 31, v4
	v_lshlrev_b64 v[4:5], 11, v[4:5]
	v_lshl_add_u64 v[4:5], v[44:45], 0, v[4:5]
	global_store_short v[4:5], v6, off offset:512
	v_mul_f32_e32 v4, 0x3c000000, v7
	v_cvt_pk_bf16_f32 v6, v4, s0
	v_or_b32_e32 v4, 35, v46
	v_ashrrev_i32_e32 v5, 31, v4
	v_lshlrev_b64 v[4:5], 11, v[4:5]
	v_lshl_add_u64 v[4:5], v[44:45], 0, v[4:5]
	global_store_short v[4:5], v6, off offset:512
	v_mul_f32_e32 v4, 0x3c000000, v8
	v_cvt_pk_bf16_f32 v6, v4, s0
	v_or_b32_e32 v4, 40, v46
	v_ashrrev_i32_e32 v5, 31, v4
	v_lshlrev_b64 v[4:5], 11, v[4:5]
	v_lshl_add_u64 v[4:5], v[44:45], 0, v[4:5]
	global_store_short v[4:5], v6, off offset:512
	v_mul_f32_e32 v4, 0x3c000000, v9
	v_cvt_pk_bf16_f32 v6, v4, s0
	v_or_b32_e32 v4, 41, v46
	v_ashrrev_i32_e32 v5, 31, v4
	v_lshlrev_b64 v[4:5], 11, v[4:5]
	v_lshl_add_u64 v[4:5], v[44:45], 0, v[4:5]
	global_store_short v[4:5], v6, off offset:512
	v_mul_f32_e32 v4, 0x3c000000, v10
	v_cvt_pk_bf16_f32 v6, v4, s0
	v_or_b32_e32 v4, 42, v46
	v_ashrrev_i32_e32 v5, 31, v4
	v_lshlrev_b64 v[4:5], 11, v[4:5]
	v_lshl_add_u64 v[4:5], v[44:45], 0, v[4:5]
	global_store_short v[4:5], v6, off offset:512
	v_mul_f32_e32 v4, 0x3c000000, v11
	v_cvt_pk_bf16_f32 v6, v4, s0
	v_or_b32_e32 v4, 43, v46
	v_ashrrev_i32_e32 v5, 31, v4
	v_lshlrev_b64 v[4:5], 11, v[4:5]
	v_lshl_add_u64 v[4:5], v[44:45], 0, v[4:5]
	global_store_short v[4:5], v6, off offset:512
	v_mul_f32_e32 v4, 0x3c000000, v12
	v_cvt_pk_bf16_f32 v6, v4, s0
	v_or_b32_e32 v4, 48, v46
	v_ashrrev_i32_e32 v5, 31, v4
	v_lshlrev_b64 v[4:5], 11, v[4:5]
	v_lshl_add_u64 v[4:5], v[44:45], 0, v[4:5]
	global_store_short v[4:5], v6, off offset:512
	v_mul_f32_e32 v4, 0x3c000000, v13
	v_cvt_pk_bf16_f32 v6, v4, s0
	v_or_b32_e32 v4, 49, v46
	v_ashrrev_i32_e32 v5, 31, v4
	v_lshlrev_b64 v[4:5], 11, v[4:5]
	v_lshl_add_u64 v[4:5], v[44:45], 0, v[4:5]
	global_store_short v[4:5], v6, off offset:512
	v_mul_f32_e32 v4, 0x3c000000, v14
	v_cvt_pk_bf16_f32 v6, v4, s0
	v_or_b32_e32 v4, 50, v46
	v_ashrrev_i32_e32 v5, 31, v4
	v_lshlrev_b64 v[4:5], 11, v[4:5]
	v_lshl_add_u64 v[4:5], v[44:45], 0, v[4:5]
	global_store_short v[4:5], v6, off offset:512
	v_mul_f32_e32 v4, 0x3c000000, v15
	v_cvt_pk_bf16_f32 v6, v4, s0
	v_or_b32_e32 v4, 51, v46
	v_ashrrev_i32_e32 v5, 31, v4
	v_lshlrev_b64 v[4:5], 11, v[4:5]
	v_lshl_add_u64 v[4:5], v[44:45], 0, v[4:5]
	global_store_short v[4:5], v6, off offset:512
	v_mul_f32_e32 v4, 0x3c000000, v16
	v_cvt_pk_bf16_f32 v6, v4, s0
	v_or_b32_e32 v4, 56, v46
	v_ashrrev_i32_e32 v5, 31, v4
	v_lshlrev_b64 v[4:5], 11, v[4:5]
	v_lshl_add_u64 v[4:5], v[44:45], 0, v[4:5]
	global_store_short v[4:5], v6, off offset:512
	v_mul_f32_e32 v4, 0x3c000000, v17
	v_cvt_pk_bf16_f32 v6, v4, s0
	v_or_b32_e32 v4, 57, v46
	v_ashrrev_i32_e32 v5, 31, v4
	v_lshlrev_b64 v[4:5], 11, v[4:5]
	v_lshl_add_u64 v[4:5], v[44:45], 0, v[4:5]
	global_store_short v[4:5], v6, off offset:512
	v_mul_f32_e32 v4, 0x3c000000, v18
	v_cvt_pk_bf16_f32 v6, v4, s0
	v_or_b32_e32 v4, 58, v46
	v_ashrrev_i32_e32 v5, 31, v4
	v_lshlrev_b64 v[4:5], 11, v[4:5]
	v_lshl_add_u64 v[4:5], v[44:45], 0, v[4:5]
	global_store_short v[4:5], v6, off offset:512
	v_mul_f32_e32 v4, 0x3c000000, v19
	v_cvt_pk_bf16_f32 v6, v4, s0
	v_or_b32_e32 v4, 59, v46
	v_ashrrev_i32_e32 v5, 31, v4
	v_lshlrev_b64 v[4:5], 11, v[4:5]
	v_lshl_add_u64 v[4:5], v[44:45], 0, v[4:5]
	global_store_short v[4:5], v6, off offset:512
	s_cbranch_scc0 .LBB0_532
